# grid barrier in phase loop: all blocks poll the monotonic top arrival counter directly (no generation-word hops)
# speedup vs baseline: 1.0129x; 1.0008x over previous
.LBB0_164:
.LBB0_165:
	s_cmp_ge_i32 s60, s61
	s_cbranch_scc1 .LBB0_532
	s_lshr_b32 s0, s3, 16
	s_and_b32 s1, s3, 0xffff
	s_and_b32 s4, 0xffff, s68
	s_add_u32 s7, s26, 0xa1d0000
	s_addc_u32 s2, s27, 0
	s_add_u32 s76, s26, 0x164d0000
	v_writelane_b32 v252, s2, 50
	s_addc_u32 s77, s27, 0
	s_lshl_b32 s2, s84, 3
	v_writelane_b32 v252, s2, 51
	s_add_u32 s2, s26, 0x60d0000
	s_addc_u32 s3, s27, 0
	s_lshl_b32 s74, s62, 3
	s_add_u32 s8, s26, 0xa1d0800
	s_addc_u32 s9, s27, 0
	s_add_u32 s10, s26, 0xa1d1000
	s_mul_i32 s6, s1, s4
	s_mul_i32 s5, s63, s62
	s_addc_u32 s63, s27, 0
	s_bfe_i32 s6, s6, 0x180000
	s_mul_i32 s0, s6, s0
	s_add_i32 s0, s0, 63
	v_bfe_u32 v2, v0, 10, 10
	v_bfe_u32 v3, v0, 20, 10
	v_and_b32_e32 v168, 0x3ff, v0
	s_andn2_b32 s0, s0, 63
	v_mad_u32_u24 v0, v3, s1, v2
	s_cmp_lg_u32 s0, 64
	v_mad_u64_u32 v[0:1], s[0:1], v0, s4, v[168:169]
	s_cselect_b64 s[90:91], -1, 0
	s_add_u32 s0, s26, 0x5ec8000
	s_addc_u32 s1, s27, 0
	s_add_u32 s92, s26, 0x5e80000
	s_addc_u32 s93, s27, 0
	s_add_u32 s94, s26, 0x5ed0000
	s_addc_u32 s95, s27, 0
	s_add_u32 s68, s26, 0x1e6d0200
	s_addc_u32 s69, s27, 0
	s_add_u32 s70, s26, 0x1e6d0400
	v_writelane_b32 v252, s2, 52
	s_addc_u32 s71, s27, 0
	s_add_u32 s80, s26, 0x1e6d0500
	v_writelane_b32 v252, s3, 53
	v_writelane_b32 v252, s0, 54
	s_addc_u32 s81, s27, 0
	s_mov_b32 s75, 0x11000
	v_writelane_b32 v252, s1, 55
	s_add_u32 s0, s26, 0x1e6d0600
	s_addc_u32 s1, s27, 0
	v_writelane_b32 v252, s0, 56
	v_or3_b32 v2, v168, v2, v3
	s_mul_i32 s65, s5, s33
	v_writelane_b32 v252, s1, 57
	s_add_u32 s0, s26, 0x1e6d0700
	s_addc_u32 s1, s27, 0
	v_writelane_b32 v252, s0, 58
	v_mbcnt_lo_u32_b32 v3, -1, 0
	v_lshrrev_b32_e32 v1, 6, v0
	v_writelane_b32 v252, s1, 59
	s_add_u32 s0, s26, 0x1e6d0800
	s_addc_u32 s1, s27, 0
	v_writelane_b32 v252, s0, 60
	v_mbcnt_hi_u32_b32 v197, -1, v3
	v_mov_b32_e32 v171, 0
	v_writelane_b32 v252, s1, 61
	s_add_u32 s0, s26, 0x1e6d0900
	s_addc_u32 s1, s27, 0
	v_writelane_b32 v252, s0, 62
	v_mov_b32_e32 v169, 0x358637bd
	v_mov_b32_e32 v173, 1
	v_writelane_b32 v252, s1, 63
	s_add_u32 s0, s26, 0x1e6d0a00
	s_addc_u32 s1, s27, 0
	v_writelane_b32 v251, s0, 0
	v_readlane_b32 s44, v252, 2
	v_mov_b32_e32 v192, 0x100
	v_writelane_b32 v251, s1, 1
	s_add_u32 s0, s26, 0x1e6d0b00
	s_addc_u32 s1, s27, 0
	v_writelane_b32 v251, s0, 2
	v_mov_b32_e32 v193, 0x3ef1014c
	v_mov_b32_e32 v194, 0x3e4ccccd
	v_writelane_b32 v251, s1, 3
	s_add_u32 s0, s26, 0x1e6d0c00
	s_addc_u32 s1, s27, 0
	v_writelane_b32 v251, s0, 4
	v_mov_b32_e32 v195, 0x1800
	v_bfrev_b32_e32 v196, 1
	v_writelane_b32 v251, s1, 5
	s_add_u32 s0, s26, 0x1e6d0d00
	s_addc_u32 s1, s27, 0
	v_writelane_b32 v251, s0, 6
	v_or_b32_e32 v198, v197, v1
	v_mov_b32_e32 v199, 0x3e38aa3b
	v_writelane_b32 v251, s1, 7
	s_add_u32 s0, s26, 0x1e6d0e00
	s_addc_u32 s1, s27, 0
	v_writelane_b32 v251, s0, 8
	v_mov_b32_e32 v172, 0xbf3a00e3
	s_movk_i32 s79, 0x60
	v_writelane_b32 v251, s1, 9
	s_add_u32 s0, s26, 0x1e6d0f00
	s_addc_u32 s1, s27, 0
	v_writelane_b32 v251, s0, 10
	s_mov_b32 s85, 0x800000
	s_mov_b32 s33, 0x30000
	v_writelane_b32 v251, s1, 11
	s_add_u32 s0, s26, 0x1e6d1000
	s_addc_u32 s1, s27, 0
	v_writelane_b32 v251, s0, 12
	s_mov_b32 s99, 0x47800000
	s_mov_b32 s89, 0x4138aa3b
	v_writelane_b32 v251, s1, 13
	s_add_u32 s0, s26, 0x1e6d1100
	s_addc_u32 s1, s27, 0
	v_writelane_b32 v251, s0, 14
	s_mov_b64 s[96:97], 0x180
	s_mov_b32 s98, 0x3e6d3388
	v_writelane_b32 v251, s1, 15
	s_add_u32 s0, s26, 0x1e6d1200
	s_addc_u32 s1, s27, 0
	v_writelane_b32 v251, s0, 16
	s_mov_b32 s72, 0x3f07dc22
	s_mov_b32 s4, 0
	v_writelane_b32 v251, s1, 17
	s_add_u32 s0, s26, 0x1e6d1300
	s_addc_u32 s1, s27, 0
	v_writelane_b32 v251, s0, 18
	s_cmp_eq_u32 s64, 15
	v_readlane_b32 s45, v252, 3
	v_writelane_b32 v251, s1, 19
	s_cselect_b64 s[0:1], -1, 0
	v_writelane_b32 v251, s0, 20
	s_cmp_eq_u32 s64, 14
	v_readlane_b32 s48, v252, 6
	v_writelane_b32 v251, s1, 21
	s_cselect_b64 s[0:1], -1, 0
	v_writelane_b32 v251, s0, 22
	s_cmp_eq_u32 s64, 13
	v_readlane_b32 s49, v252, 7
	v_writelane_b32 v251, s1, 23
	s_cselect_b64 s[0:1], -1, 0
	v_writelane_b32 v251, s0, 24
	s_cmp_eq_u32 s64, 12
	v_readlane_b32 s56, v252, 14
	v_writelane_b32 v251, s1, 25
	s_cselect_b64 s[0:1], -1, 0
	v_writelane_b32 v251, s0, 26
	s_cmp_eq_u32 s64, 11
	v_readlane_b32 s57, v252, 15
	v_writelane_b32 v251, s1, 27
	s_cselect_b64 s[0:1], -1, 0
	v_writelane_b32 v251, s0, 28
	s_cmp_eq_u32 s64, 10
	v_readlane_b32 s58, v252, 16
	v_writelane_b32 v251, s1, 29
	s_cselect_b64 s[0:1], -1, 0
	v_writelane_b32 v251, s0, 30
	s_cmp_eq_u32 s64, 9
	v_readlane_b32 s59, v252, 17
	v_writelane_b32 v251, s1, 31
	s_cselect_b64 s[0:1], -1, 0
	v_writelane_b32 v251, s0, 32
	s_cmp_eq_u32 s64, 8
	s_mov_b32 s78, s7
	v_writelane_b32 v251, s1, 33
	s_cselect_b64 s[0:1], -1, 0
	v_writelane_b32 v251, s0, 34
	s_cmp_eq_u32 s64, 7
	s_mov_b32 s73, s10
	v_writelane_b32 v251, s1, 35
	s_cselect_b64 s[0:1], -1, 0
	v_writelane_b32 v251, s0, 36
	s_cmp_eq_u32 s64, 6
	v_readlane_b32 s46, v252, 4
	v_writelane_b32 v251, s1, 37
	s_cselect_b64 s[0:1], -1, 0
	v_writelane_b32 v251, s0, 38
	s_cmp_eq_u32 s64, 5
	v_readlane_b32 s47, v252, 5
	v_writelane_b32 v251, s1, 39
	s_cselect_b64 s[0:1], -1, 0
	v_writelane_b32 v251, s0, 40
	s_cmp_eq_u32 s64, 4
	v_readlane_b32 s50, v252, 8
	v_writelane_b32 v251, s1, 41
	s_cselect_b64 s[0:1], -1, 0
	v_writelane_b32 v251, s0, 42
	s_cmp_eq_u32 s64, 3
	v_readlane_b32 s51, v252, 9
	v_writelane_b32 v251, s1, 43
	s_cselect_b64 s[0:1], -1, 0
	v_writelane_b32 v251, s0, 44
	s_cmp_eq_u32 s64, 2
	v_readlane_b32 s52, v252, 10
	v_writelane_b32 v251, s1, 45
	s_cselect_b64 s[0:1], -1, 0
	v_writelane_b32 v251, s0, 46
	s_cmp_eq_u32 s64, 1
	v_readlane_b32 s53, v252, 11
	v_writelane_b32 v251, s1, 47
	s_cselect_b64 s[0:1], -1, 0
	v_writelane_b32 v251, s0, 48
	s_cmp_eq_u32 s64, 0
	v_readlane_b32 s54, v252, 12
	v_writelane_b32 v251, s1, 49
	s_cselect_b64 s[0:1], -1, 0
	v_writelane_b32 v251, s0, 50
	v_readlane_b32 s55, v252, 13
	s_nop 0
	v_writelane_b32 v251, s1, 51
	s_lshl_b32 s0, s64, 8
	s_add_u32 s0, s66, s0
	s_addc_u32 s1, s67, 0
	s_add_u32 s2, s0, 0x1400
	s_addc_u32 s3, s1, 0
	v_writelane_b32 v251, s2, 52
	s_add_u32 s0, s0, 0x2400
	s_addc_u32 s1, s1, 0
	v_writelane_b32 v251, s3, 53
	v_writelane_b32 v251, s0, 54
	s_movk_i32 s64, 0x1000
	s_mov_b64 s[66:67], 0x100
	v_writelane_b32 v251, s1, 55
	s_add_u32 s0, s26, 0x1e6d3400
	s_addc_u32 s1, s27, 0
	v_writelane_b32 v251, s0, 56
	s_nop 1
	v_writelane_b32 v251, s1, 57
	s_add_u32 s0, s26, 0x1e6d3500
	s_addc_u32 s1, s27, 0
	v_writelane_b32 v251, s0, 58
	s_nop 1
	v_writelane_b32 v251, s1, 59
	s_lshl_b32 s0, s84, 7
	s_lshl_b32 s1, s62, 7
	v_writelane_b32 v251, s1, 60
	s_or_b32 s1, s0, 3
	v_writelane_b32 v251, s1, 61
	s_or_b32 s1, s0, 2
	v_writelane_b32 v251, s1, 62
	v_writelane_b32 v251, s0, 63
	s_or_b32 s0, s0, 1
	v_writelane_b32 v250, s0, 0
	s_add_u32 s0, s26, 0x180
	v_writelane_b32 v250, s0, 1
	s_addc_u32 s0, s27, 0
	v_writelane_b32 v250, s0, 2
	s_mov_b32 s0, 0x11200
	s_addk_i32 s0, 0x100
	v_writelane_b32 v250, s0, 3
	s_mov_b32 s0, 0x20000
	s_addk_i32 s0, 0x100
	v_writelane_b32 v250, s0, 4
	s_mov_b32 s0, 0x20004
	s_addk_i32 s0, 0x100
	v_writelane_b32 v250, s0, 5
	s_lshl_b32 s0, s84, 5
	v_writelane_b32 v250, s0, 6
	s_lshl_b32 s0, s62, 5
	v_writelane_b32 v250, s0, 7
	s_add_i32 s0, s75, 0x100
	v_writelane_b32 v250, s0, 8
	v_cmp_lt_u32_e64 s[0:1], 63, v0
	s_nop 1
	v_writelane_b32 v250, s0, 9
	s_nop 1
	v_writelane_b32 v250, s1, 10
	v_cmp_eq_u32_e64 s[0:1], 0, v2
	s_nop 1
	v_writelane_b32 v250, s0, 11
	s_nop 1
	v_writelane_b32 v250, s1, 12
	v_cmp_eq_u32_e64 s[0:1], 0, v168
	s_nop 1
	v_writelane_b32 v250, s0, 13
	s_nop 1
	v_writelane_b32 v250, s1, 14
	v_writelane_b32 v250, s7, 15
	v_writelane_b32 v250, s76, 16
	s_nop 1
	v_writelane_b32 v250, s77, 17
	v_writelane_b32 v250, s74, 18
	v_writelane_b32 v250, s8, 19
	s_nop 1
	v_writelane_b32 v250, s9, 20
	v_writelane_b32 v250, s10, 21
	v_writelane_b32 v250, s65, 22
	v_writelane_b32 v250, s68, 23
	s_nop 1
	v_writelane_b32 v250, s69, 24
	v_writelane_b32 v250, s70, 25
	s_nop 1
	v_writelane_b32 v250, s71, 26
	v_writelane_b32 v250, s80, 27
	s_nop 1
	v_writelane_b32 v250, s81, 28
	v_writelane_b32 v250, s86, 29
	s_nop 1
	v_writelane_b32 v250, s87, 30
	v_writelane_b32 v250, s63, 31
	v_writelane_b32 v250, s90, 32
	s_nop 1
	v_writelane_b32 v250, s91, 33
	v_writelane_b32 v250, s92, 34
	s_nop 1
	v_writelane_b32 v250, s93, 35
	v_writelane_b32 v250, s94, 36
	v_writelane_b32 v250, s95, 37
	v_writelane_b32 v250, s84, 38
	s_branch .LBB0_171
	s_nop 0
	s_nop 0
	s_nop 0
	s_nop 0
	s_nop 0
	s_nop 0
	s_nop 0
.LBB0_167:
	s_or_b64 exec, exec, s[8:9]
	s_waitcnt vmcnt(0)
	buffer_inv sc1
	s_waitcnt vmcnt(0)
.LBB0_168:
	s_or_b64 exec, exec, s[6:7]
	s_waitcnt lgkmcnt(0)
	s_barrier

.LBB0_501:
	v_readlane_b32 s0, v251, 52
	v_readlane_b32 s1, v251, 53
	v_cvt_f32_u32_e32 v1, v2
	v_sub_u32_e32 v4, 0, v2
	v_rcp_iflag_f32_e32 v1, v1
	s_nop 1
	global_atomic_add v3, v171, v173, s[0:1] sc0
	v_mul_f32_e32 v1, 0x4f7ffffe, v1
	v_cvt_u32_f32_e32 v1, v1
	v_mul_lo_u32 v4, v4, v1
	v_mul_hi_u32 v4, v1, v4
	v_add_u32_e32 v1, v1, v4
	s_waitcnt vmcnt(0)
	v_mul_hi_u32 v1, v3, v1
	v_mul_lo_u32 v4, v1, v2
	v_sub_u32_e32 v4, v3, v4
	v_add_u32_e32 v5, 1, v1
	v_cmp_ge_u32_e32 vcc, v4, v2
	v_add_u32_e32 v3, 1, v3
	s_nop 0
	v_cndmask_b32_e32 v1, v1, v5, vcc
	v_sub_u32_e32 v5, v4, v2
	v_cndmask_b32_e32 v4, v4, v5, vcc
	v_add_u32_e32 v5, 1, v1
	v_cmp_ge_u32_e32 vcc, v4, v2
	s_nop 1
	v_cndmask_b32_e32 v1, v1, v5, vcc
	v_mul_lo_u32 v4, v2, v1
	v_add_u32_e32 v2, v4, v2
	v_cmp_ne_u32_e32 vcc, v3, v2
	s_and_saveexec_b64 s[0:1], vcc
	s_xor_b64 s[8:9], exec, s[0:1]
	s_cbranch_execz .LBB0_515
	v_readlane_b32 s0, v251, 56
	v_readlane_b32 s1, v251, 57
	s_waitcnt lgkmcnt(0)
	v_add_u32_e32 v4, 1, v1
	v_mul_lo_u32 v4, v4, v0
	s_nop 3
	global_load_dword v0, v171, s[0:1] sc1
	s_waitcnt vmcnt(0)
	v_cmp_lt_u32_e32 vcc, v0, v4
	s_and_saveexec_b64 s[10:11], vcc
	s_cbranch_execz .LBB0_514
	s_mov_b32 s0, 1
	s_mov_b64 s[12:13], 0
	s_branch .LBB0_505

.LBB0_507:
	v_readlane_b32 s16, v251, 56
	v_readlane_b32 s17, v251, 57
	s_add_i32 s0, s0, 1
	s_mov_b64 s[18:19], -1
	s_nop 2
	global_load_dword v0, v171, s[16:17] sc1
	s_waitcnt vmcnt(0)
	v_cmp_ge_u32_e32 vcc, v0, v4
	s_orn2_b64 s[16:17], vcc, exec
	s_branch .LBB0_504

.LBB0_518:
	s_or_b64 exec, exec, s[10:11]
	s_waitcnt vmcnt(0)
	v_readfirstlane_b32 s0, v2
	v_cvt_f32_u32_e32 v2, v0
	v_sub_u32_e32 v3, 0, v0
	v_add_u32_e32 v1, s0, v1
	v_readlane_b32 s0, v251, 58
	v_rcp_iflag_f32_e32 v2, v2
	v_readlane_b32 s1, v251, 59
	s_mov_b64 s[10:11], 0
	v_mul_f32_e32 v2, 0x4f7ffffe, v2
	v_cvt_u32_f32_e32 v2, v2
	v_mul_lo_u32 v3, v3, v2
	v_mul_hi_u32 v3, v2, v3
	v_add_u32_e32 v2, v2, v3
	v_mul_hi_u32 v2, v1, v2
	v_mul_lo_u32 v3, v2, v0
	v_sub_u32_e32 v3, v1, v3
	v_cmp_ge_u32_e32 vcc, v3, v0
	v_add_u32_e32 v4, 1, v2
	v_add_u32_e32 v1, 1, v1
	v_cndmask_b32_e32 v2, v2, v4, vcc
	v_sub_u32_e32 v4, v3, v0
	v_cndmask_b32_e32 v3, v3, v4, vcc
	v_cmp_ge_u32_e32 vcc, v3, v0
	v_add_u32_e32 v3, 1, v2
	s_nop 0
	v_cndmask_b32_e32 v2, v2, v3, vcc
	v_mul_lo_u32 v3, v0, v2
	v_add_u32_e32 v0, v3, v0
	v_mov_b32_e32 v4, v0
	v_cmp_ne_u32_e32 vcc, v1, v0
	v_mov_b64_e32 v[0:1], s[0:1]
	s_and_saveexec_b64 s[8:9], vcc
	s_cbranch_execz .LBB0_530
	v_readlane_b32 s0, v251, 56
	v_readlane_b32 s1, v251, 57
	s_mov_b64 s[12:13], 0
	s_nop 3
	global_load_dword v0, v171, s[0:1] sc1
	s_waitcnt vmcnt(0)
	v_cmp_lt_u32_e32 vcc, v0, v4
	s_and_saveexec_b64 s[10:11], vcc
	s_cbranch_execz .LBB0_529
	s_mov_b32 s0, 1
	s_branch .LBB0_522
